# GU K-loops: the 4 prefetched B0 LDS reads issued back-to-back right after MFMA 17-21 instead of spread to MFMA 28
# speedup vs baseline: 1.0096x; 1.0096x over previous
; #define LAS __attribute__((address_space(3)))
; #define PG8_STAGE(bufoff, gbase, voff) do { _Pragma("unroll") for (int _i = 0; _i < 2; ++_i) \
;         __builtin_amdgcn_global_load_lds((const unsigned*)((const char*)(gbase) + (voff)[_i]), (LAS unsigned*)(lds + (bufoff) + ldsw + _i * 8192), 16, 0, 0); } while (0)
; #define PG8_LDA(dst, b, h) do { _Pragma("unroll") for (int m = 0; m < 4; ++m) _Pragma("unroll") for (int k = 0; k < 2; ++k) dst[m][k] = *(const LAS bf16x8*)(lds + PG8_SA(b, h) + aoff + m * 2048 + k * 1024); } while (0)
; #define PG8_LDB(dst, b, h) do { _Pragma("unroll") for (int n = 0; n < 2; ++n) _Pragma("unroll") for (int k = 0; k < 2; ++k) dst[n][k] = *(const LAS bf16x8*)(lds + PG8_SB(b, h) + boff + n * 2048 + k * 1024); } while (0)
; #define PG8_WAIT_V(n) asm volatile("s_waitcnt vmcnt(" #n ")" ::: "memory")
; #define PG8_WAIT_L(n) asm volatile("s_waitcnt lgkmcnt(" #n ")" ::: "memory")
; template <class Epi>
; __device__ __forceinline__ void gemm_phase(LAS unsigned char* lds, const int tid, const Gemm g, const StaticOrder& S, const Epi& E) {
;     ...
;         for (int t = 0; t < nt; t += 2) {
;             const bool last = (t == nt - 2);
;             const char* a1 = cA + (size_t)(t + 1) * kstep;
;             const char* a2 = last ? nA : cA + (size_t)(t + 2) * kstep; const char* b2 = last ? nB : cB + (size_t)(t + 2) * kstep;
;             const char* a3 = a2 + kstep; const char* b3 = b2 + kstep;
;             if constexpr (Epi::SS_LDS) { if (last) {
;                 const char* sp = (const char*)E.ss + (size_t)cur.pm * (256 * 64) + (size_t)tid * 16;
;                 __builtin_amdgcn_global_load_lds((const unsigned*)sp, (LAS unsigned*)(lds + RS_OFF + ldsw), 16, 0, 0);
;                 __builtin_amdgcn_global_load_lds((const unsigned*)(sp + 8192), (LAS unsigned*)(lds + RS_OFF + 8192 + ldsw), 16, 0, 0); } }
;     ...
;             PG8_LDB(B0, 0, 0); PG8_LDB(B1, 0, 1); PG8_SCHED; PG8_LDA(At, 0, 0); PG8_STAGE(PG8_SA(1, 1), a1 + hstepA, voffA);
;             PG8_WAIT_V(8); PG8_WAIT_L(0); PG8_BAR; PG8_MMA(0, 0, At, B0); PG8_MMA(0, 1, At, B1); PG8_BAR; PG8_SCHED;
;             PG8_LDA(At, 0, 1); PG8_STAGE(PG8_SB(0, 0), b2, voffB); PG8_STAGE(PG8_SB(0, 1), b2 + hstepB, voffB); PG8_STAGE(PG8_SA(0, 0), a2, voffA);
;             PG8_WAIT_V(8); PG8_WAIT_L(0); PG8_BAR; PG8_MMA(1, 0, At, B0); PG8_MMA(1, 1, At, B1); PG8_BAR; PG8_SCHED;
.LBB0_263:
	v_add_u32_e32 v184, s52, v151
	ds_read_b128 v[172:175], v184
	ds_read_b128 v[176:179], v184 offset:1024
	ds_read_b128 v[180:183], v184 offset:2048
	ds_read_b128 v[184:187], v184 offset:3072
	s_add_i32 s58, s58, 2
	s_add_u32 s30, s26, 0xfffc0080
	s_addc_u32 s31, s27, -1
	s_and_b64 s[28:29], s[28:29], exec
	s_cselect_b32 s31, s17, s31
	s_cselect_b32 s30, s19, s30
	s_cselect_b32 s29, s55, s57
	s_cselect_b32 s28, s56, s25
	v_lshl_add_u64 v[220:221], s[26:27], 0, v[140:141]
	s_add_i32 m0, s41, 0xc000
	ds_read_b128 v[188:191], v153
	ds_read_b128 v[192:195], v153 offset:1024
	ds_read_b128 v[196:199], v153 offset:2048
	ds_read_b128 v[200:203], v153 offset:3072
	ds_read_b128 v[204:207], v153 offset:4096
	ds_read_b128 v[208:211], v153 offset:5120
	ds_read_b128 v[212:215], v153 offset:6144
	ds_read_b128 v[216:219], v153 offset:7168
	global_load_lds_dwordx4 v[220:221], off
	v_lshl_add_u64 v[220:221], s[26:27], 0, v[138:139]
	s_add_i32 m0, s41, 0xe000
	s_nop 0
	global_load_lds_dwordx4 v[220:221], off
	s_waitcnt vmcnt(6)
	s_waitcnt lgkmcnt(0)
	s_barrier
	s_setprio 1
	v_mfma_f32_16x16x32_bf16 v[120:123], v[156:159], v[188:191], v[120:123]
	v_mfma_f32_16x16x32_bf16 v[116:119], v[164:167], v[188:191], v[116:119]
	v_mfma_f32_16x16x32_bf16 v[108:111], v[156:159], v[196:199], v[108:111]
	v_mfma_f32_16x16x32_bf16 v[100:103], v[164:167], v[196:199], v[100:103]
	v_mfma_f32_16x16x32_bf16 v[92:95], v[156:159], v[204:207], v[92:95]
	v_mfma_f32_16x16x32_bf16 v[84:87], v[164:167], v[204:207], v[84:87]
	v_mfma_f32_16x16x32_bf16 v[76:79], v[156:159], v[212:215], v[76:79]
	v_mfma_f32_16x16x32_bf16 v[68:71], v[164:167], v[212:215], v[68:71]
	v_mfma_f32_16x16x32_bf16 v[120:123], v[160:163], v[192:195], v[120:123]
	v_mfma_f32_16x16x32_bf16 v[116:119], v[168:171], v[192:195], v[116:119]
	v_mfma_f32_16x16x32_bf16 v[108:111], v[160:163], v[200:203], v[108:111]
	v_mfma_f32_16x16x32_bf16 v[100:103], v[168:171], v[200:203], v[100:103]
	v_mfma_f32_16x16x32_bf16 v[92:95], v[160:163], v[208:211], v[92:95]
	v_mfma_f32_16x16x32_bf16 v[84:87], v[168:171], v[208:211], v[84:87]
	v_mfma_f32_16x16x32_bf16 v[76:79], v[160:163], v[216:219], v[76:79]
	v_mfma_f32_16x16x32_bf16 v[68:71], v[168:171], v[216:219], v[68:71]
	v_mfma_f32_16x16x32_bf16 v[124:127], v[172:175], v[188:191], v[124:127]
	v_mfma_f32_16x16x32_bf16 v[112:115], v[180:183], v[188:191], v[112:115]
	v_mfma_f32_16x16x32_bf16 v[104:107], v[172:175], v[196:199], v[104:107]
	v_mfma_f32_16x16x32_bf16 v[96:99], v[180:183], v[196:199], v[96:99]
	v_mfma_f32_16x16x32_bf16 v[88:91], v[172:175], v[204:207], v[88:91]
	v_mfma_f32_16x16x32_bf16 v[80:83], v[180:183], v[204:207], v[80:83]
	v_mfma_f32_16x16x32_bf16 v[72:75], v[172:175], v[212:215], v[72:75]
	v_mfma_f32_16x16x32_bf16 v[64:67], v[180:183], v[212:215], v[64:67]
	v_mfma_f32_16x16x32_bf16 v[124:127], v[176:179], v[192:195], v[124:127]
	v_mfma_f32_16x16x32_bf16 v[112:115], v[184:187], v[192:195], v[112:115]
	v_mfma_f32_16x16x32_bf16 v[104:107], v[176:179], v[200:203], v[104:107]
	v_mfma_f32_16x16x32_bf16 v[96:99], v[184:187], v[200:203], v[96:99]
	v_mfma_f32_16x16x32_bf16 v[88:91], v[176:179], v[208:211], v[88:91]
	v_mfma_f32_16x16x32_bf16 v[80:83], v[184:187], v[208:211], v[80:83]
	v_mfma_f32_16x16x32_bf16 v[72:75], v[176:179], v[216:219], v[72:75]
	v_mfma_f32_16x16x32_bf16 v[64:67], v[184:187], v[216:219], v[64:67]
	s_setprio 0
	s_barrier
	s_add_i32 s59, s51, s38
	v_lshl_add_u64 v[220:221], s[28:29], 0, v[132:133]
	s_mov_b32 m0, s59
	ds_read_b128 v[188:191], v153 offset:16384
	ds_read_b128 v[192:195], v153 offset:17408
	ds_read_b128 v[196:199], v153 offset:18432
	ds_read_b128 v[200:203], v153 offset:19456
	ds_read_b128 v[204:207], v153 offset:20480
	ds_read_b128 v[208:211], v153 offset:21504
	ds_read_b128 v[212:215], v153 offset:22528
	ds_read_b128 v[216:219], v153 offset:23552
	global_load_lds_dwordx4 v[220:221], off
	s_add_i32 m0, s59, 0x2000
	s_add_u32 s60, s28, 0x40000
	v_lshl_add_u64 v[222:223], s[28:29], 0, v[128:129]
	s_addc_u32 s61, s29, 0
	s_add_i32 s59, s52, s38
	global_load_lds_dwordx4 v[222:223], off
	v_lshl_add_u64 v[224:225], s[60:61], 0, v[132:133]
	s_mov_b32 m0, s59
	v_lshl_add_u64 v[226:227], s[30:31], 0, v[130:131]
	global_load_lds_dwordx4 v[224:225], off
	v_lshl_add_u64 v[224:225], s[60:61], 0, v[128:129]
	s_add_i32 m0, s59, 0x2000
	s_nop 0
	global_load_lds_dwordx4 v[224:225], off
	v_lshl_add_u64 v[224:225], s[30:31], 0, v[134:135]
	s_mov_b32 m0, s41
	s_nop 0
	global_load_lds_dwordx4 v[224:225], off
	s_mov_b32 m0, s42
	s_nop 0
	global_load_lds_dwordx4 v[226:227], off
	s_waitcnt vmcnt(8)
	s_waitcnt lgkmcnt(0)
	s_barrier
; #define PG8_STAGE(bufoff, gbase, voff) do { _Pragma("unroll") for (int _i = 0; _i < 2; ++_i) \
;         __builtin_amdgcn_global_load_lds((const unsigned*)((const char*)(gbase) + (voff)[_i]), (LAS unsigned*)(lds + (bufoff) + ldsw + _i * 8192), 16, 0, 0); } while (0)
; #define PG8_LDA(dst, b, h) do { _Pragma("unroll") for (int m = 0; m < 4; ++m) _Pragma("unroll") for (int k = 0; k < 2; ++k) dst[m][k] = *(const LAS bf16x8*)(lds + PG8_SA(b, h) + aoff + m * 2048 + k * 1024); } while (0)
; #define PG8_LDB(dst, b, h) do { _Pragma("unroll") for (int n = 0; n < 2; ++n) _Pragma("unroll") for (int k = 0; k < 2; ++k) dst[n][k] = *(const LAS bf16x8*)(lds + PG8_SB(b, h) + boff + n * 2048 + k * 1024); } while (0)
; #define PG8_MMA(ai, bj, At, Bt) do { __builtin_amdgcn_s_setprio(1); _Pragma("unroll") for (int m = 0; m < 4; ++m) _Pragma("unroll") for (int n = 0; n < 2; ++n) _Pragma("unroll") for (int k = 0; k < 2; ++k) \
;         acc[ai][bj][m][n] = __builtin_amdgcn_mfma_f32_16x16x32_bf16(Bt[n][k], At[m][k], acc[ai][bj][m][n], 0, 0, 0); __builtin_amdgcn_s_setprio(0); } while (0)
; #define PG8_WAIT_V(n) asm volatile("s_waitcnt vmcnt(" #n ")" ::: "memory")
; #define PG8_WAIT_L(n) asm volatile("s_waitcnt lgkmcnt(" #n ")" ::: "memory")
; #define PG8_BAR __builtin_amdgcn_s_barrier()
; #define PG8_SCHED __builtin_amdgcn_sched_barrier(0)
; template <class Epi>
; __device__ __forceinline__ void gemm_phase(LAS unsigned char* lds, const int tid, const Gemm g, const StaticOrder& S, const Epi& E) {
;     ...
;             PG8_WAIT_V(8); PG8_WAIT_L(0); PG8_BAR; PG8_MMA(1, 0, At, B0); PG8_MMA(1, 1, At, B1); PG8_BAR; PG8_SCHED;
;             PG8_LDB(B0, 1, 0); PG8_LDB(B1, 1, 1); PG8_SCHED; PG8_LDA(At, 1, 0); PG8_STAGE(PG8_SA(0, 1), a2 + hstepA, voffA);
;             PG8_WAIT_V(8); PG8_WAIT_L(0); PG8_BAR; PG8_MMA(0, 0, At, B0); PG8_MMA(0, 1, At, B1); PG8_BAR; PG8_SCHED;
;             PG8_LDA(At, 1, 1); PG8_STAGE(PG8_SB(1, 0), b3, voffB); PG8_STAGE(PG8_SB(1, 1), b3 + hstepB, voffB); PG8_STAGE(PG8_SA(1, 0), a3, voffA);
	s_setprio 1
	v_mfma_f32_16x16x32_bf16 v[60:63], v[156:159], v[188:191], v[60:63]
	v_mfma_f32_16x16x32_bf16 v[52:55], v[164:167], v[188:191], v[52:55]
	v_mfma_f32_16x16x32_bf16 v[44:47], v[156:159], v[196:199], v[44:47]
	v_mfma_f32_16x16x32_bf16 v[36:39], v[164:167], v[196:199], v[36:39]
	v_mfma_f32_16x16x32_bf16 v[28:31], v[156:159], v[204:207], v[28:31]
	v_mfma_f32_16x16x32_bf16 v[20:23], v[164:167], v[204:207], v[20:23]
	v_mfma_f32_16x16x32_bf16 v[12:15], v[156:159], v[212:215], v[12:15]
	v_mfma_f32_16x16x32_bf16 v[4:7], v[164:167], v[212:215], v[4:7]
	v_mfma_f32_16x16x32_bf16 v[60:63], v[160:163], v[192:195], v[60:63]
	v_mfma_f32_16x16x32_bf16 v[52:55], v[168:171], v[192:195], v[52:55]
	v_mfma_f32_16x16x32_bf16 v[44:47], v[160:163], v[200:203], v[44:47]
	v_mfma_f32_16x16x32_bf16 v[36:39], v[168:171], v[200:203], v[36:39]
	v_mfma_f32_16x16x32_bf16 v[28:31], v[160:163], v[208:211], v[28:31]
	v_mfma_f32_16x16x32_bf16 v[20:23], v[168:171], v[208:211], v[20:23]
	v_mfma_f32_16x16x32_bf16 v[12:15], v[160:163], v[216:219], v[12:15]
	v_mfma_f32_16x16x32_bf16 v[4:7], v[168:171], v[216:219], v[4:7]
	v_mfma_f32_16x16x32_bf16 v[56:59], v[172:175], v[188:191], v[56:59]
	v_add_u32_e32 v168, 0x18000, v151
	v_mfma_f32_16x16x32_bf16 v[48:51], v[180:183], v[188:191], v[48:51]
	ds_read_b128 v[156:159], v168
	v_mfma_f32_16x16x32_bf16 v[40:43], v[172:175], v[196:199], v[40:43]
	ds_read_b128 v[160:163], v168 offset:1024
	v_mfma_f32_16x16x32_bf16 v[32:35], v[180:183], v[196:199], v[32:35]
	ds_read_b128 v[164:167], v168 offset:2048
	v_mfma_f32_16x16x32_bf16 v[24:27], v[172:175], v[204:207], v[24:27]
	ds_read_b128 v[168:171], v168 offset:3072
	v_mfma_f32_16x16x32_bf16 v[16:19], v[180:183], v[204:207], v[16:19]
	v_mfma_f32_16x16x32_bf16 v[8:11], v[172:175], v[212:215], v[8:11]
	v_mfma_f32_16x16x32_bf16 v[0:3], v[180:183], v[212:215], v[0:3]
	v_mfma_f32_16x16x32_bf16 v[56:59], v[176:179], v[192:195], v[56:59]
	v_mfma_f32_16x16x32_bf16 v[48:51], v[184:187], v[192:195], v[48:51]
	v_mfma_f32_16x16x32_bf16 v[40:43], v[176:179], v[200:203], v[40:43]
	v_mfma_f32_16x16x32_bf16 v[32:35], v[184:187], v[200:203], v[32:35]
	v_mfma_f32_16x16x32_bf16 v[24:27], v[176:179], v[208:211], v[24:27]
	v_mfma_f32_16x16x32_bf16 v[16:19], v[184:187], v[208:211], v[16:19]
	v_mfma_f32_16x16x32_bf16 v[8:11], v[176:179], v[216:219], v[8:11]
	v_mfma_f32_16x16x32_bf16 v[0:3], v[184:187], v[216:219], v[0:3]
	s_setprio 0
	s_barrier
	s_add_i32 s59, 0, 0x18000
	s_add_i32 s60, 0, 0x1c000
	v_add_u32_e32 v184, s60, v151
	ds_read_b128 v[172:175], v184
	ds_read_b128 v[176:179], v184 offset:1024
	ds_read_b128 v[180:183], v184 offset:2048
	ds_read_b128 v[184:187], v184 offset:3072
	s_add_u32 s30, s30, 0x40000
	s_addc_u32 s31, s31, 0
	s_mov_b32 m0, s43
	v_lshl_add_u64 v[228:229], s[30:31], 0, v[134:135]
	ds_read_b128 v[188:191], v153 offset:32768
	ds_read_b128 v[192:195], v153 offset:33792
	ds_read_b128 v[196:199], v153 offset:34816
	ds_read_b128 v[200:203], v153 offset:35840
	ds_read_b128 v[204:207], v153 offset:36864
	ds_read_b128 v[208:211], v153 offset:37888
	ds_read_b128 v[212:215], v153 offset:38912
	ds_read_b128 v[216:219], v153 offset:39936
	global_load_lds_dwordx4 v[228:229], off
	v_lshl_add_u64 v[228:229], s[30:31], 0, v[130:131]
	s_mov_b32 m0, s44
	s_nop 0
	global_load_lds_dwordx4 v[228:229], off
	s_waitcnt vmcnt(6)
	s_waitcnt lgkmcnt(0)
	s_barrier
	s_setprio 1
	v_mfma_f32_16x16x32_bf16 v[120:123], v[156:159], v[188:191], v[120:123]
	v_mfma_f32_16x16x32_bf16 v[116:119], v[164:167], v[188:191], v[116:119]
	v_mfma_f32_16x16x32_bf16 v[108:111], v[156:159], v[196:199], v[108:111]
	v_mfma_f32_16x16x32_bf16 v[100:103], v[164:167], v[196:199], v[100:103]
	v_mfma_f32_16x16x32_bf16 v[92:95], v[156:159], v[204:207], v[92:95]
	v_mfma_f32_16x16x32_bf16 v[84:87], v[164:167], v[204:207], v[84:87]
	v_mfma_f32_16x16x32_bf16 v[76:79], v[156:159], v[212:215], v[76:79]
	v_mfma_f32_16x16x32_bf16 v[68:71], v[164:167], v[212:215], v[68:71]
	v_mfma_f32_16x16x32_bf16 v[120:123], v[160:163], v[192:195], v[120:123]
	v_mfma_f32_16x16x32_bf16 v[116:119], v[168:171], v[192:195], v[116:119]
	v_mfma_f32_16x16x32_bf16 v[108:111], v[160:163], v[200:203], v[108:111]
	v_mfma_f32_16x16x32_bf16 v[100:103], v[168:171], v[200:203], v[100:103]
	v_mfma_f32_16x16x32_bf16 v[92:95], v[160:163], v[208:211], v[92:95]
	v_mfma_f32_16x16x32_bf16 v[84:87], v[168:171], v[208:211], v[84:87]
	v_mfma_f32_16x16x32_bf16 v[76:79], v[160:163], v[216:219], v[76:79]
	v_mfma_f32_16x16x32_bf16 v[68:71], v[168:171], v[216:219], v[68:71]
	v_mfma_f32_16x16x32_bf16 v[124:127], v[172:175], v[188:191], v[124:127]
	v_mfma_f32_16x16x32_bf16 v[112:115], v[180:183], v[188:191], v[112:115]
	v_mfma_f32_16x16x32_bf16 v[104:107], v[172:175], v[196:199], v[104:107]
	v_mfma_f32_16x16x32_bf16 v[96:99], v[180:183], v[196:199], v[96:99]
	v_mfma_f32_16x16x32_bf16 v[88:91], v[172:175], v[204:207], v[88:91]
	v_mfma_f32_16x16x32_bf16 v[80:83], v[180:183], v[204:207], v[80:83]
	v_mfma_f32_16x16x32_bf16 v[72:75], v[172:175], v[212:215], v[72:75]
	v_mfma_f32_16x16x32_bf16 v[64:67], v[180:183], v[212:215], v[64:67]
	v_mfma_f32_16x16x32_bf16 v[124:127], v[176:179], v[192:195], v[124:127]
	v_mfma_f32_16x16x32_bf16 v[112:115], v[184:187], v[192:195], v[112:115]
	v_mfma_f32_16x16x32_bf16 v[104:107], v[176:179], v[200:203], v[104:107]
	v_mfma_f32_16x16x32_bf16 v[96:99], v[184:187], v[200:203], v[96:99]
	v_mfma_f32_16x16x32_bf16 v[88:91], v[176:179], v[208:211], v[88:91]
	v_mfma_f32_16x16x32_bf16 v[80:83], v[184:187], v[208:211], v[80:83]
	v_mfma_f32_16x16x32_bf16 v[72:75], v[176:179], v[216:219], v[72:75]
	v_mfma_f32_16x16x32_bf16 v[64:67], v[184:187], v[216:219], v[64:67]
	s_setprio 0
	s_barrier
; #define PG8_STAGE(bufoff, gbase, voff) do { _Pragma("unroll") for (int _i = 0; _i < 2; ++_i) \
;         __builtin_amdgcn_global_load_lds((const unsigned*)((const char*)(gbase) + (voff)[_i]), (LAS unsigned*)(lds + (bufoff) + ldsw + _i * 8192), 16, 0, 0); } while (0)
; #define PG8_LDA(dst, b, h) do { _Pragma("unroll") for (int m = 0; m < 4; ++m) _Pragma("unroll") for (int k = 0; k < 2; ++k) dst[m][k] = *(const LAS bf16x8*)(lds + PG8_SA(b, h) + aoff + m * 2048 + k * 1024); } while (0)
; #define PG8_MMA(ai, bj, At, Bt) do { __builtin_amdgcn_s_setprio(1); _Pragma("unroll") for (int m = 0; m < 4; ++m) _Pragma("unroll") for (int n = 0; n < 2; ++n) _Pragma("unroll") for (int k = 0; k < 2; ++k) \
;         acc[ai][bj][m][n] = __builtin_amdgcn_mfma_f32_16x16x32_bf16(Bt[n][k], At[m][k], acc[ai][bj][m][n], 0, 0, 0); __builtin_amdgcn_s_setprio(0); } while (0)
; #define PG8_WAIT_V(n) asm volatile("s_waitcnt vmcnt(" #n ")" ::: "memory")
; #define PG8_WAIT_L(n) asm volatile("s_waitcnt lgkmcnt(" #n ")" ::: "memory")
; #define PG8_BAR __builtin_amdgcn_s_barrier()
; #define PG8_SCHED __builtin_amdgcn_sched_barrier(0)
; template <class Epi>
; __device__ __forceinline__ void gemm_phase(LAS unsigned char* lds, const int tid, const Gemm g, const StaticOrder& S, const Epi& E) {
;     ...
;         for (int t = 0; t < nt; t += 2) {
;             const bool last = (t == nt - 2);
;             const char* a1 = cA + (size_t)(t + 1) * kstep;
;             const char* a2 = last ? nA : cA + (size_t)(t + 2) * kstep; const char* b2 = last ? nB : cB + (size_t)(t + 2) * kstep;
;             const char* a3 = a2 + kstep; const char* b3 = b2 + kstep;
;     ...
;             PG8_LDA(At, 1, 1); PG8_STAGE(PG8_SB(1, 0), b3, voffB); PG8_STAGE(PG8_SB(1, 1), b3 + hstepB, voffB); PG8_STAGE(PG8_SA(1, 0), a3, voffA);
;             PG8_WAIT_V(8); PG8_WAIT_L(0); PG8_BAR; PG8_MMA(1, 0, At, B0); PG8_MMA(1, 1, At, B1); PG8_BAR; PG8_SCHED;
	s_add_i32 s30, s59, s38
	v_lshl_add_u64 v[220:221], v[220:221], 0, s[12:13]
	s_mov_b32 m0, s30
	ds_read_b128 v[188:191], v153 offset:49152
	ds_read_b128 v[192:195], v153 offset:50176
	ds_read_b128 v[196:199], v153 offset:51200
	ds_read_b128 v[200:203], v153 offset:52224
	ds_read_b128 v[204:207], v153 offset:53248
	ds_read_b128 v[208:211], v153 offset:54272
	ds_read_b128 v[212:215], v153 offset:55296
	ds_read_b128 v[216:219], v153 offset:56320
	global_load_lds_dwordx4 v[220:221], off
	s_add_i32 m0, s30, 0x2000
	s_add_u32 s28, s28, 0x40080
	v_lshl_add_u64 v[220:221], v[222:223], 0, s[12:13]
	s_addc_u32 s29, s29, 0
	s_add_i32 s30, s60, s38
	global_load_lds_dwordx4 v[220:221], off
	v_lshl_add_u64 v[220:221], s[28:29], 0, v[132:133]
	s_mov_b32 m0, s30
	s_nop 0
	global_load_lds_dwordx4 v[220:221], off
	v_lshl_add_u64 v[220:221], s[28:29], 0, v[128:129]
	s_add_i32 m0, s30, 0x2000
	s_nop 0
	global_load_lds_dwordx4 v[220:221], off
	v_lshl_add_u64 v[220:221], v[224:225], 0, s[12:13]
	s_mov_b32 m0, s47
	s_nop 0
	global_load_lds_dwordx4 v[220:221], off
	v_lshl_add_u64 v[220:221], v[226:227], 0, s[12:13]
	s_mov_b32 m0, s48
	s_nop 0
	global_load_lds_dwordx4 v[220:221], off
	s_add_u32 s25, s25, 0x100
	s_addc_u32 s57, s57, 0
	s_add_u32 s26, s26, 0x100
	s_addc_u32 s27, s27, 0
	s_cmp_eq_u32 s49, s58
	s_cselect_b64 s[28:29], -1, 0
	s_waitcnt vmcnt(8)
	s_waitcnt lgkmcnt(0)
	s_barrier
	s_setprio 1
	v_mfma_f32_16x16x32_bf16 v[60:63], v[156:159], v[188:191], v[60:63]
	v_mfma_f32_16x16x32_bf16 v[52:55], v[164:167], v[188:191], v[52:55]
	v_mfma_f32_16x16x32_bf16 v[44:47], v[156:159], v[196:199], v[44:47]
	v_mfma_f32_16x16x32_bf16 v[36:39], v[164:167], v[196:199], v[36:39]
	v_mfma_f32_16x16x32_bf16 v[28:31], v[156:159], v[204:207], v[28:31]
	v_mfma_f32_16x16x32_bf16 v[20:23], v[164:167], v[204:207], v[20:23]
	v_mfma_f32_16x16x32_bf16 v[12:15], v[156:159], v[212:215], v[12:15]
	v_mfma_f32_16x16x32_bf16 v[4:7], v[164:167], v[212:215], v[4:7]
	v_mfma_f32_16x16x32_bf16 v[60:63], v[160:163], v[192:195], v[60:63]
	v_mfma_f32_16x16x32_bf16 v[52:55], v[168:171], v[192:195], v[52:55]
	v_mfma_f32_16x16x32_bf16 v[44:47], v[160:163], v[200:203], v[44:47]
	v_mfma_f32_16x16x32_bf16 v[36:39], v[168:171], v[200:203], v[36:39]
	v_mfma_f32_16x16x32_bf16 v[28:31], v[160:163], v[208:211], v[28:31]
	v_mfma_f32_16x16x32_bf16 v[20:23], v[168:171], v[208:211], v[20:23]
	v_mfma_f32_16x16x32_bf16 v[12:15], v[160:163], v[216:219], v[12:15]
	v_mfma_f32_16x16x32_bf16 v[4:7], v[168:171], v[216:219], v[4:7]
	v_mfma_f32_16x16x32_bf16 v[56:59], v[172:175], v[188:191], v[56:59]
	v_add_u32_e32 v168, s51, v151
	v_mfma_f32_16x16x32_bf16 v[48:51], v[180:183], v[188:191], v[48:51]
	ds_read_b128 v[156:159], v168
	v_mfma_f32_16x16x32_bf16 v[40:43], v[172:175], v[196:199], v[40:43]
	ds_read_b128 v[160:163], v168 offset:1024
	v_mfma_f32_16x16x32_bf16 v[32:35], v[180:183], v[196:199], v[32:35]
	ds_read_b128 v[164:167], v168 offset:2048
	v_mfma_f32_16x16x32_bf16 v[24:27], v[172:175], v[204:207], v[24:27]
	ds_read_b128 v[168:171], v168 offset:3072
	v_mfma_f32_16x16x32_bf16 v[16:19], v[180:183], v[204:207], v[16:19]
	v_mfma_f32_16x16x32_bf16 v[8:11], v[172:175], v[212:215], v[8:11]
	v_mfma_f32_16x16x32_bf16 v[0:3], v[180:183], v[212:215], v[0:3]
	v_mfma_f32_16x16x32_bf16 v[56:59], v[176:179], v[192:195], v[56:59]
	v_mfma_f32_16x16x32_bf16 v[48:51], v[184:187], v[192:195], v[48:51]
	v_mfma_f32_16x16x32_bf16 v[40:43], v[176:179], v[200:203], v[40:43]
	v_mfma_f32_16x16x32_bf16 v[32:35], v[184:187], v[200:203], v[32:35]
	v_mfma_f32_16x16x32_bf16 v[24:27], v[176:179], v[208:211], v[24:27]
	v_mfma_f32_16x16x32_bf16 v[16:19], v[184:187], v[208:211], v[16:19]
	v_mfma_f32_16x16x32_bf16 v[8:11], v[176:179], v[216:219], v[8:11]
	v_mfma_f32_16x16x32_bf16 v[0:3], v[184:187], v[216:219], v[0:3]
	s_setprio 0
	s_barrier
	s_cmp_ge_i32 s58, s46
	s_cbranch_scc1 .LBB0_266
	s_cmp_lg_u32 s49, s58
	s_cbranch_scc1 .LBB0_263
	s_branch .Lrs_1
